# weight convert split three ways: c_in, b_out and w2[1] converted by the 128 workgroups that have no tile in the last round of GEMM_IN(B); late set in SCAN_C as before
# baseline (speedup 1.0000x reference)
; DI u16 f2bf(float x) { return (u16)(pk2bf(x, 0.f) & 0xffffu); }
; #define PG8_WAIT_V(n) asm volatile("s_waitcnt vmcnt(" #n ")" ::: "memory")
; #define PG8_BAR __builtin_amdgcn_s_barrier()
; #define WSEL(i) if (t >= wTileStart(i)) { K = cK[i]; N = cN[i]; base = wTileStart(i); off = wOff(i); soff = cSrcOff[i]; bi = cBase[i]; }
; template <class Epi, class Sched>
; __device__ __forceinline__ void gemm_phase(PG8_LAS unsigned char* lds, const Gemm g, const Sched& S, const Epi& E, const int tid) {
;     ...
;     PG8_WAIT_V(0);
;     if (wr == 0) PG8_BAR;
;     PG8_BAR;
; DI CvtTile cvt_locate(const Ctx& p, int t) {
;   int K = cK[0], N = cN[0], base = 0; unsigned off = 0, soff = 0; int bi = 0;
;     ...
;   WSEL(1) WSEL(2) WSEL(3) WSEL(4) WSEL(5) WSEL(6) WSEL(7) WSEL(8) WSEL(9) WSEL(10) WSEL(11) WSEL(12) WSEL(13) WSEL(14) WSEL(15)
;     ...
;   const float* src = p.wbase[0];
; #pragma unroll
;   for (int q = 1; q < 8; ++q) if (bi == q) src = p.wbase[q];
;   const int lt = t - base, nkt = K / 64;
;   CvtTile c; c.src = src + soff; c.K = K; c.N = N; c.k0 = (lt % nkt) * 64; c.n0 = (lt / nkt) * 64; c.off = off;
;   return c;
; }
; DI void phase_convert(int wv_, int vb_, int nvb_, char* ws_, const Ctx& p, char* smem) {
;   float* tile = (float*)smem;
;   const int tid = tidx(wv_);
;   const int ty = tid >> 4, tx = tid & 15;
;   constexpr int total = wTileStart(16);
;   const int trips_ = (total + nvb_ - 1) / nvb_;
;     ...
;   CvtTile cur = cvt_locate(p, (vb_ < total) ? vb_ : total - 1);
;   float4 v[4];
;   CVT_LOAD(cur, v)
;   for (int k_ = 0; k_ < trips_; ++k_) {
;     const int tn = vb_ + (k_ + 1) * nvb_;
;     const CvtTile nxt = cvt_locate(p, (tn < total) ? tn : total - 1);
;     float4 vn[4];
;     CVT_LOAD(nxt, vn)
; #pragma unroll
;     for (int i = 0; i < 4; ++i) { float* d = tile + (ty + 16 * i) * 65 + tx * 4; d[0] = v[i].x; d[1] = v[i].y; d[2] = v[i].z; d[3] = v[i].w; }
;     __syncthreads();
;     {
;       const int n = tid >> 2, kq = tid & 3;
;       bf16x8 o0, o1;
; #pragma unroll
;       for (int j = 0; j < 8; ++j) { o0[j] = (short)f2bf(tile[(kq * 16 + j) * 65 + n]); o1[j] = (short)f2bf(tile[(kq * 16 + 8 + j) * 65 + n]); }
;       u16* dst = (u16*)(ws_ + WS_WT) + (size_t)cur.off + (size_t)(cur.n0 + n) * cur.K + cur.k0 + kq * 16;
;       *(bf16x8*)dst = o0; *(bf16x8*)(dst + 8) = o1;
;     }
;     __syncthreads();
.LBB0_725:
	s_waitcnt vmcnt(0) lgkmcnt(0)
	s_barrier
	v_readlane_b32 s0, v254, 14
	s_cmp_lt_u32 s0, 0x100
	s_cbranch_scc1 .Lcvt_mid_skip
	s_mov_b64 s[56:57], s[54:55]
	v_readlane_b32 s54, v254, 46
	v_readlane_b32 s55, v254, 47
	v_readlane_b32 s44, v254, 14
	v_readlane_b32 s35, v254, 56
	s_sub_i32 s44, s44, 256
	s_sub_i32 s35, s35, 256
	s_mov_b32 s10, s33
	v_lshl_add_u32 v81, s10, 6, v204
	v_lshrrev_b32_e32 v74, 4, v81
	v_and_b32_e32 v75, 15, v81
	v_lshlrev_b32_e32 v75, 2, v75
	v_lshrrev_b32_e32 v78, 2, v81
	v_and_b32_e32 v79, 3, v81
	v_mul_u32_u24_e32 v76, 65, v74
	v_add_u32_e32 v76, v76, v75
	v_lshl_add_u32 v76, v76, 2, v214
	v_mul_u32_u24_e32 v77, 0x410, v79
	v_add_u32_e32 v77, v77, v78
	v_lshl_add_u32 v77, v77, 2, v214
	v_lshlrev_b32_e32 v79, 5, v79
	s_mov_b32 s34, 0
.Lcvtc_loop:
	s_mul_i32 s52, s34, s35
	s_add_i32 s52, s52, s44
	s_min_u32 s52, s52, 0x93f
	s_mov_b32 s0, 4
	s_mov_b32 s1, 0x400
	s_mov_b32 s2, 3
	s_mov_b32 s3, 0
	s_mov_b32 s7, 0xc40000
	s_mov_b32 s11, 0
	s_cmp_ge_u32 s52, 0x100
	s_cselect_b32 s0, 4, s0
	s_cselect_b32 s1, 0x1010, s1
	s_cselect_b32 s2, 4, s2
	s_cselect_b32 s3, 0, s3
	s_cselect_b32 s7, 0xd40000, s7
	s_cselect_b32 s11, 0x100, s11
	s_cmp_ge_u32 s52, 0x540
	s_cselect_b32 s0, 6, s0
	s_cselect_b32 s1, 0x400, s1
	s_cselect_b32 s2, 7, s2
	s_cselect_b32 s3, 0x400000, s3
	s_cselect_b32 s7, 0x2680000, s7
	s_cselect_b32 s11, 0x540, s11
	s_lshl_b32 s15, s2, 3
	s_add_i32 s15, s15, 0x60
	s_load_dwordx2 s[18:19], s[54:55], s15
	s_sub_i32 s15, s52, s11
	s_lshl_b32 s2, 1, s0
	s_add_i32 s2, s2, -1
	s_and_b32 s2, s15, s2
	s_lshl_b32 s2, s2, 6
	s_lshr_b32 s15, s15, s0
	s_lshl_b32 s15, s15, 6
	s_mov_b32 s6, s0
	s_add_i32 s11, s0, 6
	s_lshl_b32 s11, s15, s11
	s_add_i32 s11, s11, s7
	s_add_i32 s11, s11, s2
	s_lshl_b32 s11, s11, 1
	s_add_u32 s4, s78, s11
	s_addc_u32 s5, s79, 0
	s_mul_i32 s7, s2, s1
	s_add_i32 s7, s7, s3
	s_add_i32 s7, s7, s15
	s_lshl_b32 s7, s7, 2
	s_lshl_b32 s3, s1, 6
	v_mul_u32_u24_e32 v81, s1, v74
	v_add_u32_e32 v81, v81, v75
	v_lshlrev_b32_e32 v80, 2, v81
	v_add_u32_e32 v81, s15, v75
	v_mov_b32_e32 v2, 0
	v_mov_b32_e32 v3, 0
	v_mov_b32_e32 v4, 0
	v_mov_b32_e32 v5, 0
	v_mov_b32_e32 v6, 0
	v_mov_b32_e32 v7, 0
	v_mov_b32_e32 v8, 0
	v_mov_b32_e32 v9, 0
	v_mov_b32_e32 v10, 0
	v_mov_b32_e32 v11, 0
	v_mov_b32_e32 v12, 0
	v_mov_b32_e32 v13, 0
	v_mov_b32_e32 v14, 0
	v_mov_b32_e32 v15, 0
	v_mov_b32_e32 v16, 0
	v_mov_b32_e32 v17, 0
	s_waitcnt lgkmcnt(0)
	s_add_u32 s18, s18, s7
	s_addc_u32 s19, s19, 0
	v_cmp_gt_u32_e32 vcc, s1, v81
	s_and_saveexec_b64 s[100:101], vcc
	global_load_dwordx4 v[2:5], v80, s[18:19]
	s_add_u32 s18, s18, s3
	s_addc_u32 s19, s19, 0
	global_load_dwordx4 v[6:9], v80, s[18:19]
	s_add_u32 s18, s18, s3
	s_addc_u32 s19, s19, 0
	global_load_dwordx4 v[10:13], v80, s[18:19]
	s_add_u32 s18, s18, s3
	s_addc_u32 s19, s19, 0
	global_load_dwordx4 v[14:17], v80, s[18:19]
	s_mov_b64 exec, s[100:101]
	s_waitcnt vmcnt(0)
	ds_write_b32 v76, v2
	ds_write_b32 v76, v3 offset:4
	ds_write_b32 v76, v4 offset:8
	ds_write_b32 v76, v5 offset:12
	ds_write_b32 v76, v6 offset:4160
	ds_write_b32 v76, v7 offset:4164
	ds_write_b32 v76, v8 offset:4168
	ds_write_b32 v76, v9 offset:4172
	ds_write_b32 v76, v10 offset:8320
	ds_write_b32 v76, v11 offset:8324
	ds_write_b32 v76, v12 offset:8328
	ds_write_b32 v76, v13 offset:8332
	ds_write_b32 v76, v14 offset:12480
	ds_write_b32 v76, v15 offset:12484
	ds_write_b32 v76, v16 offset:12488
	ds_write_b32 v76, v17 offset:12492
	s_waitcnt lgkmcnt(0)
	s_barrier
	ds_read_b32 v50, v77
	ds_read_b32 v51, v77 offset:260
	ds_read_b32 v52, v77 offset:520
	ds_read_b32 v53, v77 offset:780
	ds_read_b32 v54, v77 offset:1040
	ds_read_b32 v55, v77 offset:1300
	ds_read_b32 v56, v77 offset:1560
	ds_read_b32 v57, v77 offset:1820
	ds_read_b32 v58, v77 offset:2080
	ds_read_b32 v59, v77 offset:2340
	ds_read_b32 v60, v77 offset:2600
	ds_read_b32 v61, v77 offset:2860
	ds_read_b32 v62, v77 offset:3120
	ds_read_b32 v63, v77 offset:3380
	ds_read_b32 v64, v77 offset:3640
	ds_read_b32 v65, v77 offset:3900
	s_add_i32 s15, s6, 7
	v_lshlrev_b32_e32 v82, s15, v78
	v_add_u32_e32 v82, v82, v79
	s_waitcnt lgkmcnt(0)
	v_cvt_pk_bf16_f32 v66, v50, v51
	v_cvt_pk_bf16_f32 v67, v52, v53
	v_cvt_pk_bf16_f32 v68, v54, v55
	v_cvt_pk_bf16_f32 v69, v56, v57
	v_cvt_pk_bf16_f32 v70, v58, v59
	v_cvt_pk_bf16_f32 v71, v60, v61
	v_cvt_pk_bf16_f32 v72, v62, v63
	v_cvt_pk_bf16_f32 v73, v64, v65
	global_store_dwordx4 v82, v[66:69], s[4:5]
	global_store_dwordx4 v82, v[70:73], s[4:5] offset:16
	s_barrier
	s_add_i32 s34, s34, 1
	s_mul_i32 s15, s34, s35
	s_cmp_lt_u32 s15, 0x940
	s_cbranch_scc1 .Lcvtc_loop
	s_waitcnt vmcnt(0)
	s_mov_b64 s[54:55], s[56:57]
.Lcvt_mid_skip:
	s_nop 0
	s_nop 0
	s_nop 0
.LBB0_726:
	s_mov_b64 s[2:3], 0

; #define WSEL(i) if (t >= wTileStart(i)) { K = cK[i]; N = cN[i]; base = wTileStart(i); off = wOff(i); soff = cSrcOff[i]; bi = cBase[i]; }
; DI CvtTile cvt_locate(const Ctx& p, int t) {
;   int K = cK[0], N = cN[0], base = 0; unsigned off = 0, soff = 0; int bi = 0;
;     ...
;   WSEL(1) WSEL(2) WSEL(3) WSEL(4) WSEL(5) WSEL(6) WSEL(7) WSEL(8) WSEL(9) WSEL(10) WSEL(11) WSEL(12) WSEL(13) WSEL(14) WSEL(15)
;     ...
;   const float* src = p.wbase[0];
; #pragma unroll
;   for (int q = 1; q < 8; ++q) if (bi == q) src = p.wbase[q];
;   const int lt = t - base, nkt = K / 64;
;   CvtTile c; c.src = src + soff; c.K = K; c.N = N; c.k0 = (lt % nkt) * 64; c.n0 = (lt / nkt) * 64; c.off = off;
;   return c;
; }
.Lcvta_loop:
	s_mul_i32 s52, s34, s35
	s_add_i32 s52, s52, s44
	s_min_u32 s52, s52, 0x133f
	s_mov_b32 s0, 4
	s_mov_b32 s1, 0x1200
	s_mov_b32 s2, 0
	s_mov_b32 s3, 0
	s_mov_b32 s7, 0
	s_mov_b32 s11, 0
	s_cmp_ge_u32 s52, 0x480
	s_cselect_b32 s0, 3, s0
	s_cselect_b32 s1, 0x400, s1
	s_cselect_b32 s2, 1, s2
	s_cselect_b32 s3, 0, s3
	s_cselect_b32 s7, 0x900000, s7
	s_cselect_b32 s11, 0x480, s11
	s_cmp_ge_u32 s52, 0x500
	s_cselect_b32 s0, 4, s0
	s_cselect_b32 s1, 0x848, s1
	s_cselect_b32 s2, 2, s2
	s_cselect_b32 s3, 0, s3
	s_cselect_b32 s7, 0xa00000, s7
	s_cselect_b32 s11, 0x500, s11
	s_cmp_ge_u32 s52, 0x740
	s_cselect_b32 s0, 4, s0
	s_cselect_b32 s1, 0x1000, s1
	s_cselect_b32 s2, 6, s2
	s_cselect_b32 s3, 0, s3
	s_cselect_b32 s7, 0x1280000, s7
	s_cselect_b32 s11, 0x740, s11
	s_cmp_ge_u32 s52, 0xb40
	s_cselect_b32 s0, 4, s0
	s_cselect_b32 s1, 0x1000, s1
	s_cselect_b32 s2, 6, s2
	s_cselect_b32 s3, 0x400000, s3
	s_cselect_b32 s7, 0x1680000, s7
	s_cselect_b32 s11, 0xb40, s11
	s_cmp_ge_u32 s52, 0xf40
	s_cselect_b32 s0, 6, s0
	s_cselect_b32 s1, 0x400, s1
	s_cselect_b32 s2, 7, s2
	s_cselect_b32 s3, 0, s3
	s_cselect_b32 s7, 0x2280000, s7
	s_cselect_b32 s11, 0xf40, s11
	s_lshl_b32 s15, s2, 3
	s_add_i32 s15, s15, 0x60
	s_load_dwordx2 s[18:19], s[54:55], s15
	s_sub_i32 s15, s52, s11
	s_lshl_b32 s2, 1, s0
	s_add_i32 s2, s2, -1
	s_and_b32 s2, s15, s2
	s_lshl_b32 s2, s2, 6
	s_lshr_b32 s15, s15, s0
	s_lshl_b32 s15, s15, 6
	s_mov_b32 s6, s0
	s_add_i32 s11, s0, 6
	s_lshl_b32 s11, s15, s11
	s_add_i32 s11, s11, s7
	s_add_i32 s11, s11, s2
	s_lshl_b32 s11, s11, 1
	s_add_u32 s4, s78, s11
	s_addc_u32 s5, s79, 0
	s_mul_i32 s7, s2, s1
	s_add_i32 s7, s7, s3
	s_add_i32 s7, s7, s15
	s_lshl_b32 s7, s7, 2
	s_lshl_b32 s3, s1, 6
	v_mul_u32_u24_e32 v81, s1, v74
	v_add_u32_e32 v81, v81, v75
	v_lshlrev_b32_e32 v80, 2, v81
	v_add_u32_e32 v81, s15, v75
	v_mov_b32_e32 v2, 0
	v_mov_b32_e32 v3, 0
	v_mov_b32_e32 v4, 0
	v_mov_b32_e32 v5, 0
	v_mov_b32_e32 v6, 0
	v_mov_b32_e32 v7, 0
	v_mov_b32_e32 v8, 0
	v_mov_b32_e32 v9, 0
	v_mov_b32_e32 v10, 0
	v_mov_b32_e32 v11, 0
	v_mov_b32_e32 v12, 0
	v_mov_b32_e32 v13, 0
	v_mov_b32_e32 v14, 0
	v_mov_b32_e32 v15, 0
	v_mov_b32_e32 v16, 0
	v_mov_b32_e32 v17, 0
	s_waitcnt lgkmcnt(0)
	s_add_u32 s18, s18, s7
	s_addc_u32 s19, s19, 0
	v_cmp_gt_u32_e32 vcc, s1, v81
	s_and_saveexec_b64 s[100:101], vcc
	global_load_dwordx4 v[2:5], v80, s[18:19]
	s_add_u32 s18, s18, s3
	s_addc_u32 s19, s19, 0
	global_load_dwordx4 v[6:9], v80, s[18:19]
	s_add_u32 s18, s18, s3
	s_addc_u32 s19, s19, 0
	global_load_dwordx4 v[10:13], v80, s[18:19]
	s_add_u32 s18, s18, s3
	s_addc_u32 s19, s19, 0
	global_load_dwordx4 v[14:17], v80, s[18:19]
	s_mov_b64 exec, s[100:101]
	s_waitcnt vmcnt(0)
	ds_write_b32 v76, v2
	ds_write_b32 v76, v3 offset:4
	ds_write_b32 v76, v4 offset:8
	ds_write_b32 v76, v5 offset:12
	ds_write_b32 v76, v6 offset:4160
	ds_write_b32 v76, v7 offset:4164
	ds_write_b32 v76, v8 offset:4168
	ds_write_b32 v76, v9 offset:4172
	ds_write_b32 v76, v10 offset:8320
	ds_write_b32 v76, v11 offset:8324
	ds_write_b32 v76, v12 offset:8328
	ds_write_b32 v76, v13 offset:8332
	ds_write_b32 v76, v14 offset:12480
	ds_write_b32 v76, v15 offset:12484
	ds_write_b32 v76, v16 offset:12488
	ds_write_b32 v76, v17 offset:12492
	s_waitcnt lgkmcnt(0)
	s_barrier
	ds_read_b32 v50, v77
	ds_read_b32 v51, v77 offset:260
	ds_read_b32 v52, v77 offset:520
	ds_read_b32 v53, v77 offset:780
	ds_read_b32 v54, v77 offset:1040
	ds_read_b32 v55, v77 offset:1300
	ds_read_b32 v56, v77 offset:1560
	ds_read_b32 v57, v77 offset:1820
	ds_read_b32 v58, v77 offset:2080
	ds_read_b32 v59, v77 offset:2340
	ds_read_b32 v60, v77 offset:2600
	ds_read_b32 v61, v77 offset:2860
	ds_read_b32 v62, v77 offset:3120
	ds_read_b32 v63, v77 offset:3380
	ds_read_b32 v64, v77 offset:3640
	ds_read_b32 v65, v77 offset:3900
	s_add_i32 s15, s6, 7
	v_lshlrev_b32_e32 v82, s15, v78
	v_add_u32_e32 v82, v82, v79
	s_waitcnt lgkmcnt(0)
	v_cvt_pk_bf16_f32 v66, v50, v51
	v_cvt_pk_bf16_f32 v67, v52, v53
	v_cvt_pk_bf16_f32 v68, v54, v55
	v_cvt_pk_bf16_f32 v69, v56, v57
	v_cvt_pk_bf16_f32 v70, v58, v59
	v_cvt_pk_bf16_f32 v71, v60, v61
	v_cvt_pk_bf16_f32 v72, v62, v63
	v_cvt_pk_bf16_f32 v73, v64, v65
	global_store_dwordx4 v82, v[66:69], s[4:5]
	global_store_dwordx4 v82, v[70:73], s[4:5] offset:16
	s_barrier
	s_add_i32 s34, s34, 1
	s_mul_i32 s15, s34, s35
	s_cmp_lt_u32 s15, 0x1340
	s_cbranch_scc1 .Lcvta_loop
	s_waitcnt vmcnt(0)
	s_branch .LBB0_842
